# v15 + P5 entry staggered in four groups of workgroups (rank&3 x ~0.55 us) so the epilogue store bursts of an XCD do not coincide
# baseline (speedup 1.0000x reference)
; #define PG8_WAIT_V(n) asm volatile("s_waitcnt vmcnt(" #n ")" ::: "memory")
; template <class Epi, class Sched, bool ALIGN_EPI = false, bool SP2 = false>
; __device__ __forceinline__ void gemm_phase(PG8_LAS unsigned char* lds, const Gemm g, const Sched& S, const Epi& E) {
;     const int tid = threadIdx.x, wid = __builtin_amdgcn_readfirstlane(tid >> 6), lane = tid & 63, wr = wid >> 2, wc = wid & 3, fr = lane & 15, fq = lane >> 4;
;     const int K = g.K, nt = K / BK;
;     unsigned voffA[2], voffB[2];
; #pragma unroll
;     for (int i = 0; i < 2; ++i) { int R, C; stage_rc(tid * 16 + i * 8192, R, C); const int Rb = Epi::PERM ? ((R & ~31) + perm32(R & 31)) : R;
;         voffA[i] = (unsigned)(R * K + C) * 2u; voffB[i] = (unsigned)(Rb * K + C) * 2u; }
;     const size_t kstep = (size_t)(BK * 2);
;     const size_t hstep = (size_t)HALF * K * 2;
;     const size_t tstep = 2 * hstep;
;     const unsigned ldsw = (unsigned)wid * 1024u;
;     const int aoff = lds_byte(wr * 64 + fr, fq * 8), boff = lds_byte(wc * 32 + fr, fq * 8);
;     ...
;     Unit cur, nxt; int ui = 0;
;     if (!S.next(0, cur)) return;
;     f32x4 acc[2][2][4][2];
; #pragma unroll
;     for (int a = 0; a < 2; ++a)
; #pragma unroll
;         for (int b = 0; b < 2; ++b)
; #pragma unroll
;             for (int m = 0; m < 4; ++m)
; #pragma unroll
;                 for (int n = 0; n < 2; ++n) acc[a][b][m][n] = (f32x4){0.f, 0.f, 0.f, 0.f};
;     bf16x8 At[4][2], B0[2][2], B1[2][2];
;     const char* cA = (const char*)(cur.seg ? g.A1 : g.A0) + (size_t)cur.pm * tstep; const char* cB = (const char*)(cur.seg ? g.B1 : g.B0) + (size_t)cur.pn * tstep;
;     S.a_ready(cur);
;     if constexpr (SP2) {
;         PG8_STAGE(PG8_SB(0, 0), cB, voffB); PG8_STAGE(PG8_SB(0, 1), cB + hstep, voffB); PG8_STAGE(PG8_SA(0, 0), cA, voffA); PG8_STAGE(PG8_SA(0, 1), cA + hstep, voffA);
;         if (wr == 1) PG8_BAR;
;         PG8_WAIT_V(2); PG8_BAR;
;         PG8_STAGE(PG8_SB(1, 0), cB + kstep, voffB); PG8_STAGE(PG8_SA(1, 0), cA + kstep, voffA); PG8_STAGE(PG8_SB(1, 1), cB + hstep + kstep, voffB);
; __global__ void __launch_bounds__(NWAVES * 64, 2) hybrid_fwd(Args args) {
;     ...
;     if (IN(5)) {
;         pg8::Gemm g{X1B, X1B, Wgu, Wgu, M, FF2, D}; pg8::StaticOrder S; S.init(M, FF2, G, vbx);
;         pg8::EpiGateUp E{SS, ACT};
;         pg8::gemm_phase<pg8::EpiGateUp, pg8::StaticOrder, true, true>(L, g, S, E);
.LBB0_761:
	s_cmp_lt_i32 s28, 6
	s_cselect_b64 s[0:1], -1, 0
	s_and_b64 s[0:1], s[0:1], s[4:5]
	s_andn2_b64 vcc, exec, s[0:1]
	s_cbranch_vccnz .LBB0_778
	s_cmpk_gt_i32 s2, 0xaff
	v_readfirstlane_b32 s3, v164
	s_cbranch_scc1 .LBB0_778
	s_bfe_u32 s67, s2, 0x20003
	s_cmp_eq_u32 s67, 0
	s_cbranch_scc1 .Lp5_stg
.Lp5_stl:
	s_sleep 18
	s_sub_i32 s67, s67, 1
	s_cmp_lg_u32 s67, 0
	s_cbranch_scc1 .Lp5_stl
.Lp5_stg:
	v_and_b32_e32 v240, 7, v164
	v_bfe_u32 v241, v164, 4, 3
	v_xor_b32_e32 v240, v240, v241
	v_lshlrev_b32_e32 v240, 4, v240
	v_lshrrev_b32_e32 v241, 3, v164
	v_lshl_or_b32 v242, v241, 11, v240
	v_add_u32_e32 v243, 0x20000, v242
	v_bfe_u32 v244, v164, 5, 2
	v_lshlrev_b32_e32 v244, 3, v244
	v_bfe_u32 v245, v164, 7, 1
	v_lshl_or_b32 v244, v245, 2, v244
	v_bfe_u32 v245, v164, 3, 2
	v_or_b32_e32 v244, v244, v245
	v_bfe_u32 v245, v164, 8, 1
	v_lshl_or_b32 v244, v245, 5, v244
	v_lshl_or_b32 v244, v244, 11, v240
	v_add_u32_e32 v245, 0x20000, v244
	v_and_b32_e32 v246, 15, v164
	v_bfe_u32 v247, v164, 4, 2
	v_bfe_u32 v248, v164, 1, 3
	v_xor_b32_e32 v247, v247, v248
	v_lshlrev_b32_e32 v247, 4, v247
	v_lshl_or_b32 v246, v246, 7, v247
	v_lshrrev_b32_e32 v0, 5, v164
	v_lshrrev_b32_e32 v2, 1, v164
	v_and_b32_e32 v0, 4, v0
	v_bfe_u32 v1, v164, 2, 2
	v_and_b32_e32 v2, 24, v2
	v_or3_b32 v0, v0, v1, v2
	v_lshlrev_b32_e32 v1, 4, v164
	v_add_u32_e32 v8, 0x2000, v1
	v_lshrrev_b32_e32 v2, 7, v8
	s_movk_i32 s4, 0xe0
	v_and_b32_e32 v4, 32, v164
	s_waitcnt lgkmcnt(0)
	v_and_or_b32 v3, v2, s4, v0
	v_bitop3_b32 v9, v1, v4, 48 bitop3:0x6c
	v_and_b32_e32 v10, 64, v164
	v_bfe_u32 v11, v164, 2, 4
	s_movk_i32 s4, 0xf0
	v_or_b32_e32 v1, v9, v10
	v_and_or_b32 v2, v2, s4, v11
	v_mov_b32_e32 v130, v243
	v_lshrrev_b32_e32 v2, 3, v164
	s_movk_i32 s4, 0x60
	v_and_or_b32 v0, v2, s4, v0
	s_movk_i32 s4, 0x70
	v_mov_b32_e32 v132, v244
	v_and_or_b32 v0, v2, s4, v11
	s_mul_hi_i32 s4, s2, 0x2e8ba2e9
	s_lshr_b32 s7, s4, 31
	s_ashr_i32 s4, s4, 9
	s_add_i32 s4, s4, s7
	s_mulk_i32 s4, 0xb00
	s_sub_i32 s4, s2, s4
	s_sext_i32_i16 s7, s4
	s_bfe_u32 s7, s7, 0x3001c
	s_add_i32 s7, s4, s7
	s_sext_i32_i16 s8, s7
	s_and_b32 s7, s7, 0xfff8
	s_lshr_b32 s5, s3, 6
	s_sub_i32 s4, s4, s7
	s_lshr_b32 s16, s3, 8
	s_lshl_b32 s6, s5, 10
	s_ashr_i32 s8, s8, 3
	s_sext_i32_i16 s7, s4
	s_cmp_lt_i32 s7, 0
	s_movk_i32 s7, 0x161
	s_cselect_b32 s9, s7, 0x160
	s_mul_i32 s4, s4, s9
	s_add_i32 s4, s4, s8
	s_sext_i32_i16 s8, s4
	s_mulk_i32 s8, 0xba3
	s_lshr_b32 s9, s8, 31
	s_ashr_i32 s8, s8, 19
	s_add_i32 s8, s8, s9
	s_lshl_b32 s9, s8, 3
	s_mulk_i32 s8, 0xb0
	s_sub_i32 s8, s4, s8
	s_sext_i32_i16 s4, s8
	s_bfe_u32 s4, s4, 0x3001c
	s_add_i32 s14, s8, s4
	s_sext_i32_i16 s4, s14
	s_and_b32 s14, s14, 0xfff8
	s_sub_i32 s8, s8, s14
	s_sext_i32_i16 s8, s8
	s_lshr_b32 s4, s4, 3
	s_add_i32 s36, s9, s8
	s_ashr_i32 s37, s36, 31
	s_bfe_i64 s[8:9], s[4:5], 0x100000
	s_lshl_b64 s[14:15], s[36:37], 19
	s_lshl_b64 s[8:9], s[8:9], 19
	s_add_u32 s40, s60, s8
	s_addc_u32 s41, s61, s9
	s_add_i32 s8, s6, 0
	s_add_i32 m0, s8, 0x10000
	v_mov_b32_e32 v128, v245
	global_load_lds_dwordx4 v132, s[40:41]
	s_add_i32 m0, s8, 0x12000
	s_add_u32 s18, s40, 0x40000
	global_load_lds_dwordx4 v128, s[40:41]
	s_addc_u32 s19, s41, 0
	s_add_i32 m0, s8, 0x14000
	v_mov_b32_e32 v134, v242
	global_load_lds_dwordx4 v132, s[18:19]
	s_add_i32 m0, s8, 0x16000
	s_add_u32 s38, s10, s14
	s_addc_u32 s39, s11, s15
	s_add_i32 s9, s8, 0x2000
	global_load_lds_dwordx4 v128, s[18:19]
	s_mov_b32 m0, s8
	s_add_u32 s14, s38, 0x40000
	global_load_lds_dwordx4 v134, s[38:39]
	s_mov_b32 m0, s9
	s_addc_u32 s15, s39, 0
	s_add_i32 s34, s8, 0x4000
	global_load_lds_dwordx4 v130, s[38:39]
	s_mov_b32 m0, s34
	s_add_i32 s35, s8, 0x6000
	global_load_lds_dwordx4 v134, s[14:15]
	s_mov_b32 m0, s35
	v_mov_b32_e32 v133, 0
	global_load_lds_dwordx4 v130, s[14:15]
	v_mov_b32_e32 v129, v133
	v_mov_b32_e32 v135, v133
	v_mov_b32_e32 v131, v133
	s_cmp_eq_u32 s16, 1
	s_mov_b64 s[64:65], s[48:49]
	s_mov_b32 s37, 0
	v_lshl_add_u64 v[6:7], s[40:41], 0, v[132:133]
	v_lshl_add_u64 v[4:5], s[40:41], 0, v[128:129]
	v_lshl_add_u64 v[0:1], s[38:39], 0, v[134:135]
	s_cselect_b64 s[14:15], -1, 0
	s_cmp_lg_u32 s16, 1
	v_lshl_add_u64 v[2:3], s[38:39], 0, v[130:131]
	s_cbranch_scc1 .LBB0_765
	s_barrier
